# final out stores sc1 nt (write-through: less dirty L2 to flush at kernel end); on top of v064
# baseline (speedup 1.0000x reference)
; __device__ __forceinline__ void final_tile(const Unit& u, const h16* HB, float* ssq, unsigned* cnt, const float* fnw, float* out, int tid) {
;     ...
;     for (int rb = wave; rb < BM; rb += 64) {
;         h16x4 hv[8]; float sq[8];
; #pragma unroll
;         for (int q = 0; q < 8; ++q) { const size_t row = (size_t)u.pm * BM + rb + 8 * q; hv[q] = *(const h16x4*)(HB + row * D + c0); sq[q] = __hip_atomic_load(ssq + row, __ATOMIC_RELAXED, __HIP_MEMORY_SCOPE_AGENT); }
; #pragma unroll
;         for (int q = 0; q < 8; ++q) { const size_t row = (size_t)u.pm * BM + rb + 8 * q; const float rs = rsqrtf(sq[q] * (1.f / D) + EPS);
;             f32x4 o; o[0] = (float)hv[q][0] * rs * w4[0]; o[1] = (float)hv[q][1] * rs * w4[1]; o[2] = (float)hv[q][2] * rs * w4[2]; o[3] = (float)hv[q][3] * rs * w4[3];
;             *(f32x4*)(out + row * D + c0) = o; }
.LBB0_613:
	v_add_co_u32_e32 v26, vcc, 0xfff90000, v14
	v_add_co_u32_e64 v22, s[6:7], s43, v16
	s_nop 0
	v_addc_co_u32_e32 v27, vcc, -1, v15, vcc
	v_add_co_u32_e32 v36, vcc, 0xfffa0000, v14
	global_load_dwordx2 v[38:39], v[26:27], off
	global_load_dword v41, v[18:19], off offset:-128 sc1
	v_addc_co_u32_e32 v37, vcc, -1, v15, vcc
	v_add_co_u32_e32 v26, vcc, 0xfffb0000, v14
	global_load_dwordx2 v[42:43], v[36:37], off
	global_load_dword v40, v[18:19], off offset:-96 sc1
	v_addc_co_u32_e32 v27, vcc, -1, v15, vcc
	v_add_co_u32_e32 v36, vcc, 0xfffc0000, v14
	global_load_dwordx2 v[48:49], v[26:27], off
	global_load_dword v51, v[18:19], off offset:-64 sc1
	v_addc_co_u32_e32 v37, vcc, -1, v15, vcc
	v_add_co_u32_e32 v26, vcc, 0xfffd0000, v14
	global_load_dwordx2 v[52:53], v[36:37], off
	global_load_dword v50, v[18:19], off offset:-32 sc1
	v_addc_co_u32_e32 v27, vcc, -1, v15, vcc
	v_add_co_u32_e32 v36, vcc, 0xfffe0000, v14
	global_load_dwordx2 v[54:55], v[26:27], off
	global_load_dword v57, v[18:19], off sc1
	v_addc_co_u32_e32 v37, vcc, -1, v15, vcc
	v_add_co_u32_e32 v26, vcc, 0xffff0000, v14
	global_load_dwordx2 v[58:59], v[36:37], off
	global_load_dword v56, v[18:19], off offset:32 sc1
	v_addc_co_u32_e32 v27, vcc, -1, v15, vcc
	global_load_dwordx2 v[36:37], v[26:27], off
	global_load_dword v63, v[18:19], off offset:64 sc1
	global_load_dwordx2 v[64:65], v[14:15], off
	global_load_dword v62, v[18:19], off offset:96 sc1
	v_addc_co_u32_e64 v23, s[6:7], 0, v17, s[6:7]
	v_add_co_u32_e64 v24, s[6:7], s44, v16
	v_mov_b64_e32 v[20:21], s[24:25]
	s_nop 0
	v_addc_co_u32_e64 v25, s[6:7], 0, v17, s[6:7]
	v_add_co_u32_e64 v28, s[6:7], s45, v16
	v_add_u32_e32 v35, 64, v35
	s_nop 0
	v_addc_co_u32_e64 v29, s[6:7], 0, v17, s[6:7]
	v_add_co_u32_e64 v30, s[6:7], s48, v16
	v_add_co_u32_e32 v60, vcc, 0xe0000, v16
	s_nop 0
	v_addc_co_u32_e64 v31, s[6:7], 0, v17, s[6:7]
	v_add_co_u32_e64 v44, s[6:7], s49, v16
	v_addc_co_u32_e32 v61, vcc, 0, v17, vcc
	s_nop 0
	v_addc_co_u32_e64 v45, s[6:7], 0, v17, s[6:7]
	v_add_co_u32_e64 v46, s[6:7], s50, v16
	v_lshl_add_u64 v[14:15], v[14:15], 0, s[26:27]
	s_nop 0
	v_addc_co_u32_e64 v47, s[6:7], 0, v17, s[6:7]
	v_cmp_lt_i32_e64 s[6:7], s51, v35
	s_or_b64 s[40:41], s[6:7], s[40:41]
	v_lshl_add_u64 v[18:19], v[18:19], 0, s[34:35]
	s_waitcnt vmcnt(15)
	v_cvt_f32_f16_e32 v26, v38
	v_cvt_f32_f16_sdwa v27, v38 dst_sel:DWORD dst_unused:UNUSED_PAD src0_sel:WORD_1
	v_cvt_f32_f16_e32 v38, v39
	v_cvt_f32_f16_sdwa v39, v39 dst_sel:DWORD dst_unused:UNUSED_PAD src0_sel:WORD_1
	s_waitcnt vmcnt(13)
	v_cvt_f32_f16_e32 v66, v42
	s_waitcnt vmcnt(12)
	v_pk_fma_f32 v[40:41], v[40:41], s[22:23], v[20:21] op_sel_hi:[1,0,0]
	v_cvt_f32_f16_sdwa v67, v42 dst_sel:DWORD dst_unused:UNUSED_PAD src0_sel:WORD_1
	v_mul_f32_e32 v70, 0x4b800000, v41
	v_mul_f32_e32 v71, 0x4b800000, v40
	v_cmp_gt_f32_e32 vcc, s42, v40
	v_cmp_gt_f32_e64 s[6:7], s42, v41
	v_cvt_f32_f16_e32 v42, v43
	v_cndmask_b32_e32 v71, v40, v71, vcc
	v_cndmask_b32_e64 v70, v41, v70, s[6:7]
	v_rsq_f32_e32 v78, v70
	s_waitcnt vmcnt(8)
	v_pk_fma_f32 v[40:41], v[50:51], s[22:23], v[20:21] op_sel_hi:[1,0,0]
	v_rsq_f32_e32 v79, v71
	v_mul_f32_e32 v72, 0x4b800000, v41
	v_mul_f32_e32 v73, 0x4b800000, v40
	v_cmp_gt_f32_e64 s[8:9], s42, v40
	v_cmp_gt_f32_e64 s[10:11], s42, v41
	v_cvt_f32_f16_sdwa v43, v43 dst_sel:DWORD dst_unused:UNUSED_PAD src0_sel:WORD_1
	v_cndmask_b32_e64 v73, v40, v73, s[8:9]
	v_cndmask_b32_e64 v72, v41, v72, s[10:11]
	v_rsq_f32_e32 v80, v72
	s_waitcnt vmcnt(4)
	v_pk_fma_f32 v[40:41], v[56:57], s[22:23], v[20:21] op_sel_hi:[1,0,0]
	v_rsq_f32_e32 v81, v73
	v_mul_f32_e32 v82, 0x4b800000, v41
	v_mul_f32_e32 v83, 0x4b800000, v40
	v_cmp_gt_f32_e64 s[12:13], s42, v40
	s_waitcnt vmcnt(0)
; __device__ __forceinline__ void final_tile(const Unit& u, const h16* HB, float* ssq, unsigned* cnt, const float* fnw, float* out, int tid) {
;     ...
; #pragma unroll
;         for (int q = 0; q < 8; ++q) { const size_t row = (size_t)u.pm * BM + rb + 8 * q; const float rs = rsqrtf(sq[q] * (1.f / D) + EPS);
;             f32x4 o; o[0] = (float)hv[q][0] * rs * w4[0]; o[1] = (float)hv[q][1] * rs * w4[1]; o[2] = (float)hv[q][2] * rs * w4[2]; o[3] = (float)hv[q][3] * rs * w4[3];
;             *(f32x4*)(out + row * D + c0) = o; }
	v_pk_fma_f32 v[20:21], v[62:63], s[22:23], v[20:21] op_sel_hi:[1,0,0]
	v_cmp_gt_f32_e64 s[14:15], s42, v41
	v_cvt_f32_f16_e32 v72, v36
	v_cvt_f32_f16_sdwa v73, v36 dst_sel:DWORD dst_unused:UNUSED_PAD src0_sel:WORD_1
	v_cvt_f32_f16_e32 v74, v37
	v_cvt_f32_f16_sdwa v75, v37 dst_sel:DWORD dst_unused:UNUSED_PAD src0_sel:WORD_1
	v_cndmask_b32_e64 v36, v41, v82, s[14:15]
	v_cndmask_b32_e64 v37, v40, v83, s[12:13]
	v_mul_f32_e32 v40, 0x4b800000, v21
	v_cmp_gt_f32_e64 s[18:19], s42, v21
	v_cvt_f32_f16_e32 v68, v48
	v_cvt_f32_f16_sdwa v69, v48 dst_sel:DWORD dst_unused:UNUSED_PAD src0_sel:WORD_1
	v_cvt_f32_f16_e32 v48, v49
	v_cvt_f32_f16_sdwa v49, v49 dst_sel:DWORD dst_unused:UNUSED_PAD src0_sel:WORD_1
	v_cvt_f32_f16_e32 v50, v52
	v_cvt_f32_f16_sdwa v51, v52 dst_sel:DWORD dst_unused:UNUSED_PAD src0_sel:WORD_1
	v_cvt_f32_f16_e32 v52, v53
	v_cvt_f32_f16_sdwa v53, v53 dst_sel:DWORD dst_unused:UNUSED_PAD src0_sel:WORD_1
	v_cvt_f32_f16_sdwa v63, v64 dst_sel:DWORD dst_unused:UNUSED_PAD src0_sel:WORD_1
	v_cvt_f32_f16_e32 v62, v64
	v_cvt_f32_f16_sdwa v77, v65 dst_sel:DWORD dst_unused:UNUSED_PAD src0_sel:WORD_1
	v_cvt_f32_f16_e32 v76, v65
	v_mul_f32_e32 v41, 0x4b800000, v20
	v_cmp_gt_f32_e64 s[16:17], s42, v20
	v_mul_f32_e32 v64, 0x45800000, v78
	v_mul_f32_e32 v65, 0x45800000, v79
	v_rsq_f32_e32 v82, v36
	v_cndmask_b32_e64 v21, v21, v40, s[18:19]
	v_rsq_f32_e32 v83, v37
	v_cndmask_b32_e64 v37, v20, v41, s[16:17]
	v_cndmask_b32_e64 v20, v78, v64, s[6:7]
	v_cndmask_b32_e32 v36, v79, v65, vcc
	v_rsq_f32_e32 v64, v21
	v_cvt_f32_f16_e32 v70, v54
	v_cvt_f32_f16_sdwa v71, v54 dst_sel:DWORD dst_unused:UNUSED_PAD src0_sel:WORD_1
	v_cvt_f32_f16_e32 v54, v55
	v_cvt_f32_f16_sdwa v55, v55 dst_sel:DWORD dst_unused:UNUSED_PAD src0_sel:WORD_1
	v_rsq_f32_e32 v65, v37
	v_pk_mul_f32 v[26:27], v[20:21], v[26:27] op_sel_hi:[0,1]
	v_pk_mul_f32 v[20:21], v[20:21], v[38:39] op_sel_hi:[0,1]
	v_pk_mul_f32 v[40:41], v[36:37], v[66:67] op_sel_hi:[0,1]
	v_pk_mul_f32 v[42:43], v[36:37], v[42:43] op_sel_hi:[0,1]
	v_mul_f32_e32 v66, 0x45800000, v80
	v_mul_f32_e32 v67, 0x45800000, v81
	v_cvt_f32_f16_e32 v56, v58
	v_cvt_f32_f16_sdwa v57, v58 dst_sel:DWORD dst_unused:UNUSED_PAD src0_sel:WORD_1
	v_cvt_f32_f16_e32 v58, v59
	v_cvt_f32_f16_sdwa v59, v59 dst_sel:DWORD dst_unused:UNUSED_PAD src0_sel:WORD_1
	v_pk_mul_f32 v[38:39], v[2:3], v[20:21]
	v_pk_mul_f32 v[36:37], v[0:1], v[26:27]
	v_pk_mul_f32 v[42:43], v[2:3], v[42:43]
	v_pk_mul_f32 v[40:41], v[0:1], v[40:41]
	v_cndmask_b32_e64 v20, v80, v66, s[10:11]
	v_cndmask_b32_e64 v26, v81, v67, s[8:9]
	global_store_dwordx4 v[16:17], v[36:39], off sc1 nt
	global_store_dwordx4 v[22:23], v[40:43], off sc1 nt
	v_lshl_add_u64 v[16:17], v[16:17], 0, s[28:29]
	v_pk_mul_f32 v[36:37], v[20:21], v[68:69] op_sel_hi:[0,1]
	v_pk_mul_f32 v[20:21], v[20:21], v[48:49] op_sel_hi:[0,1]
	v_pk_mul_f32 v[40:41], v[26:27], v[50:51] op_sel_hi:[0,1]
	v_pk_mul_f32 v[26:27], v[26:27], v[52:53] op_sel_hi:[0,1]
	v_mul_f32_e32 v42, 0x45800000, v82
	v_mul_f32_e32 v43, 0x45800000, v83
	v_pk_mul_f32 v[22:23], v[2:3], v[20:21]
	v_pk_mul_f32 v[20:21], v[0:1], v[36:37]
	v_pk_mul_f32 v[38:39], v[2:3], v[26:27]
	v_pk_mul_f32 v[36:37], v[0:1], v[40:41]
	v_cndmask_b32_e64 v26, v82, v42, s[14:15]
	v_mul_f32_e32 v41, 0x45800000, v64
	v_cndmask_b32_e64 v40, v83, v43, s[12:13]
	v_mul_f32_e32 v42, 0x45800000, v65
	global_store_dwordx4 v[24:25], v[20:23], off sc1 nt
	global_store_dwordx4 v[28:29], v[36:39], off sc1 nt
	v_cndmask_b32_e64 v28, v64, v41, s[18:19]
	v_pk_mul_f32 v[20:21], v[26:27], v[70:71] op_sel_hi:[0,1]
	v_pk_mul_f32 v[22:23], v[26:27], v[54:55] op_sel_hi:[0,1]
	v_pk_mul_f32 v[24:25], v[40:41], v[56:57] op_sel_hi:[0,1]
	v_pk_mul_f32 v[26:27], v[40:41], v[58:59] op_sel_hi:[0,1]
	v_cndmask_b32_e64 v36, v65, v42, s[16:17]
	v_pk_mul_f32 v[22:23], v[2:3], v[22:23]
	v_pk_mul_f32 v[20:21], v[0:1], v[20:21]
	v_pk_mul_f32 v[38:39], v[28:29], v[72:73] op_sel_hi:[0,1]
	v_pk_mul_f32 v[28:29], v[28:29], v[74:75] op_sel_hi:[0,1]
	v_pk_mul_f32 v[26:27], v[2:3], v[26:27]
	v_pk_mul_f32 v[24:25], v[0:1], v[24:25]
	v_pk_mul_f32 v[40:41], v[36:37], v[62:63] op_sel_hi:[0,1]
	v_pk_mul_f32 v[36:37], v[36:37], v[76:77] op_sel_hi:[0,1]
	global_store_dwordx4 v[30:31], v[20:23], off sc1 nt
	global_store_dwordx4 v[44:45], v[24:27], off sc1 nt
	s_nop 0
	v_pk_mul_f32 v[22:23], v[2:3], v[28:29]
	v_pk_mul_f32 v[20:21], v[0:1], v[38:39]
	v_pk_mul_f32 v[26:27], v[2:3], v[36:37]
	v_pk_mul_f32 v[24:25], v[0:1], v[40:41]
	global_store_dwordx4 v[46:47], v[20:23], off sc1 nt
	global_store_dwordx4 v[60:61], v[24:27], off sc1 nt
	s_andn2_b64 exec, exec, s[40:41]
	s_cbranch_execnz .LBB0_613
	s_branch .LBB0_587
